# hazard spacing fix (v_cmp->v_cndmask) in sample attention; same optimizations
# baseline (speedup 1.0000x reference)
; __device__ __forceinline__ unsigned pk2(float lo, float hi) { const f32x2_ v = {lo, hi}; return __builtin_bit_cast(unsigned, __builtin_convertvector(v, bf16x2_)); }
; __device__ __forceinline__ void attn_sample_unit(const PP P, LAS unsigned char* lds, int b, int h) {
;     ...
;     for (int kb = kb0; kb < kb1; ++kb) {
;         f32x4 s[2]; int kof[2];
; #pragma unroll
;         for (int sub = 0; sub < 2; ++sub) { const int key0 = kb * 32 + sub * 16; const bool valid = key0 < nkeys; kof[sub] = (valid && key0 >= 2048) ? 65536 + b * 16 + (key0 - 2048) : b * 2048 + (valid ? key0 : 0);
;             const size_t kr = (size_t)keybase + kof[sub] + fr;
;             const bf16x8 a0 = *(const bf16x8*)(KN + kr * 512 + h * 64 + fq * 8), a1 = *(const bf16x8*)(KN + kr * 512 + h * 64 + 32 + fq * 8), a2 = *(const bf16x8*)(KPEB + kr * 32 + fq * 8);
;             f32x4 acc = {0.f, 0.f, 0.f, 0.f}; acc = mfma16(a0, Qb[0], acc); acc = mfma16(a1, Qb[1], acc); acc = mfma16(a2, Qb[2], acc);
;             if (!valid) acc = (f32x4){-INFINITY, -INFINITY, -INFINITY, -INFINITY};
;             s[sub] = acc; }
;         float mx = fmaxf(fmaxf(fmaxf(s[0][0], s[0][1]), fmaxf(s[0][2], s[0][3])), fmaxf(fmaxf(s[1][0], s[1][1]), fmaxf(s[1][2], s[1][3])));
;         mx = fmaxf(mx, xor16_get(mx)); mx = xor32_max(mx);
;         const float mnew = fmaxf(m, mx); const float alpha = __builtin_amdgcn_exp2f(m - mnew); m = mnew;
;         float p[8]; float ps = 0.f;
; #pragma unroll
;         for (int j = 0; j < 4; ++j) { p[j] = __builtin_amdgcn_exp2f(s[0][j] - mnew); p[4 + j] = __builtin_amdgcn_exp2f(s[1][j] - mnew); ps += p[j] + p[4 + j]; }
;         lsum = lsum * alpha + ps;
;         u32x4 pw; pw.x = pk2(p[0], p[1]); pw.y = pk2(p[2], p[3]); pw.z = pk2(p[4], p[5]); pw.w = pk2(p[6], p[7]);
;         const bf16x8 Pb = __builtin_bit_cast(bf16x8, pw);
; #pragma unroll
;         for (int nt = 0; nt < 4; ++nt) { const bf16* vrow = VT + (size_t)(h * 64 + 16 * nt + fr) * NK + keybase + fq * 4;
;             const s16x4 a = *(const s16x4*)(vrow + kof[0]), c = *(const s16x4*)(vrow + kof[1]);
;             bf16x8 va; va[0] = a[0]; va[1] = a[1]; va[2] = a[2]; va[3] = a[3]; va[4] = c[0]; va[5] = c[1]; va[6] = c[2]; va[7] = c[3];
;             O[nt] = mfma16(va, Pb, O[nt] * alpha); }
;     }
.LBB0_54:
	v_add_u32_e32 v200, 16, v51
	v_cmp_gt_i32_e32 vcc, 0x810, v200
	s_nop 1
	v_cndmask_b32_e32 v200, 0, v200, vcc
	v_add_u32_e32 v228, s36, v200
	v_ashrrev_i32_e32 v229, 31, v228
	v_lshl_add_u64 v[230:231], v[228:229], 0, v[108:109]
	v_lshlrev_b64 v[232:233], 10, v[230:231]
	v_lshl_add_u64 v[232:233], v[48:49], 0, v[232:233]
	global_load_dwordx4 v[200:203], v[232:233], off
	global_load_dwordx4 v[204:207], v[232:233], off offset:64
	v_lshlrev_b64 v[230:231], 6, v[230:231]
	v_lshl_add_u64 v[230:231], v[110:111], 0, v[230:231]
	global_load_dwordx4 v[208:211], v[230:231], off
	v_lshlrev_b64 v[234:235], 1, v[228:229]
	s_movk_i32 s14, 0x41
	v_cmp_gt_i32_e32 vcc, s14, v59
	v_cmp_eq_u32_e64 s[14:15], 64, v59
	v_mov_b32_e32 v31, s35
	v_cndmask_b32_e32 v30, 0, v51, vcc
	v_add_u32_e32 v30, s36, v30
	v_cndmask_b32_e64 v60, v30, v31, s[14:15]
	v_ashrrev_i32_e32 v61, 31, v60
	v_lshl_add_u64 v[52:53], v[60:61], 0, v[108:109]
	v_lshlrev_b64 v[30:31], 10, v[52:53]
	v_lshl_add_u64 v[34:35], v[48:49], 0, v[30:31]
	global_load_dwordx4 v[30:33], v[34:35], off
	s_nop 0
	global_load_dwordx4 v[34:37], v[34:35], off offset:64
	v_lshlrev_b64 v[52:53], 6, v[52:53]
	v_lshl_add_u64 v[52:53], v[110:111], 0, v[52:53]
	global_load_dwordx4 v[52:55], v[52:53], off
	s_movk_i32 s14, 0x810
	v_mov_b32_e32 v62, v24
	v_mov_b32_e32 v24, v50
	v_lshlrev_b64 v[60:61], 1, v[60:61]
	v_lshl_add_u64 v[236:237], v[40:41], 0, v[60:61]
	global_load_dwordx2 v[212:213], v[236:237], off
	v_lshl_add_u64 v[238:239], v[40:41], 0, v[234:235]
	global_load_dwordx2 v[214:215], v[238:239], off
	v_lshl_add_u64 v[236:237], v[42:43], 0, v[60:61]
	global_load_dwordx2 v[216:217], v[236:237], off
	v_lshl_add_u64 v[238:239], v[42:43], 0, v[234:235]
	global_load_dwordx2 v[218:219], v[238:239], off
	v_lshl_add_u64 v[236:237], v[44:45], 0, v[60:61]
	global_load_dwordx2 v[220:221], v[236:237], off
	v_lshl_add_u64 v[238:239], v[44:45], 0, v[234:235]
	global_load_dwordx2 v[222:223], v[238:239], off
	v_lshl_add_u64 v[236:237], v[46:47], 0, v[60:61]
	global_load_dwordx2 v[224:225], v[236:237], off
	v_lshl_add_u64 v[238:239], v[46:47], 0, v[234:235]
	global_load_dwordx2 v[226:227], v[238:239], off
	s_waitcnt vmcnt(10)
	v_mfma_f32_16x16x32_bf16 v[30:33], v[30:33], v[26:29], 0
	s_waitcnt vmcnt(9)
	v_mfma_f32_16x16x32_bf16 v[30:33], v[34:37], v[20:23], v[30:33]
	s_waitcnt vmcnt(8)
	v_mfma_f32_16x16x32_bf16 v[30:33], v[52:55], v[16:19], v[30:33]
	s_nop 7
	v_cndmask_b32_e32 v58, v166, v30, vcc
	v_add_u32_e32 v30, 16, v51
	v_cndmask_b32_e32 v56, v166, v32, vcc
	v_cndmask_b32_e32 v57, v166, v33, vcc
	v_cndmask_b32_e32 v63, v166, v31, vcc
	v_cmp_gt_i32_e32 vcc, s14, v30
	v_max_f32_e32 v50, v56, v56
	v_add_u32_e32 v51, 32, v51
	v_cndmask_b32_e32 v30, 0, v30, vcc
	v_add_u32_e32 v36, s36, v30
	v_ashrrev_i32_e32 v37, 31, v36
	v_lshl_add_u64 v[34:35], v[36:37], 0, v[108:109]
	v_lshlrev_b64 v[30:31], 10, v[34:35]
	v_lshl_add_u64 v[52:53], v[48:49], 0, v[30:31]
	v_lshlrev_b64 v[34:35], 6, v[34:35]
	v_lshl_add_u64 v[34:35], v[110:111], 0, v[34:35]
	v_max_f32_e32 v34, v63, v63
	v_max_f32_e32 v35, v58, v58
	v_max_f32_e32 v34, v35, v34
	v_max_f32_e32 v35, v57, v57
	v_max_f32_e32 v35, v50, v35
	s_waitcnt vmcnt(8)
	v_mfma_f32_16x16x32_bf16 v[30:33], v[200:203], v[26:29], 0
	v_mfma_f32_16x16x32_bf16 v[30:33], v[204:207], v[20:23], v[30:33]
	v_mfma_f32_16x16x32_bf16 v[30:33], v[208:211], v[16:19], v[30:33]
	s_nop 7
	v_cndmask_b32_e32 v32, v166, v32, vcc
	v_cndmask_b32_e32 v33, v166, v33, vcc
	v_max_f32_e32 v50, v33, v33
	v_max_f32_e32 v52, v32, v32
	v_cndmask_b32_e32 v31, v166, v31, vcc
	v_cndmask_b32_e32 v30, v166, v30, vcc
	v_max_f32_e32 v50, v52, v50
	v_max3_f32 v50, v30, v31, v50
	v_max3_f32 v34, v34, v35, v50
	ds_swizzle_b32 v35, v34 offset:swizzle(SWAP,16)
	s_waitcnt lgkmcnt(0)
	v_max_f32_e32 v35, v35, v35
	v_max_f32_e32 v34, v34, v35
	v_mov_b32_e32 v35, v34
	s_nop 1
	v_permlane32_swap_b32_e32 v34, v35
	v_max3_f32 v50, v24, v34, v35
	v_sub_f32_e32 v34, v24, v50
	v_sub_f32_e32 v24, v58, v50
	v_exp_f32_e32 v35, v24
	v_sub_f32_e32 v24, v30, v50
	v_sub_f32_e32 v30, v31, v50
	v_exp_f32_e32 v64, v24
	v_sub_f32_e32 v24, v63, v50
	v_exp_f32_e32 v52, v30
	v_exp_f32_e32 v24, v24
	v_sub_f32_e32 v30, v56, v50
	v_exp_f32_e32 v31, v30
	v_sub_f32_e32 v30, v32, v50
	v_exp_f32_e32 v63, v30
	v_sub_f32_e32 v30, v57, v50
	v_add_f32_e32 v53, v64, v35
	v_exp_f32_e32 v56, v30
	v_sub_f32_e32 v30, v33, v50
	v_cvt_pk_bf16_f32 v32, v64, v52
	v_lshlrev_b64 v[64:65], 1, v[36:37]
	v_exp_f32_e32 v54, v30
	v_exp_f32_e32 v58, v34
	v_cvt_pk_bf16_f32 v30, v35, v24
	v_add_f32_e32 v55, v63, v31
	v_cvt_pk_bf16_f32 v31, v31, v56
	v_cvt_pk_bf16_f32 v33, v63, v54
	v_pk_mul_f32 v[14:15], v[14:15], v[58:59] op_sel_hi:[1,0]
	v_pk_mul_f32 v[12:13], v[12:13], v[58:59] op_sel_hi:[1,0]
	v_pk_mul_f32 v[10:11], v[10:11], v[58:59] op_sel_hi:[1,0]
	v_pk_mul_f32 v[8:9], v[8:9], v[58:59] op_sel_hi:[1,0]
	v_pk_mul_f32 v[6:7], v[6:7], v[58:59] op_sel_hi:[1,0]
	v_pk_mul_f32 v[4:5], v[4:5], v[58:59] op_sel_hi:[1,0]
	v_pk_mul_f32 v[2:3], v[2:3], v[58:59] op_sel_hi:[1,0]
	v_pk_mul_f32 v[0:1], v[0:1], v[58:59] op_sel_hi:[1,0]
	v_add_u32_e32 v59, 1, v59
	v_cmp_ge_i32_e32 vcc, v59, v149
	s_or_b64 s[26:27], vcc, s[26:27]
	s_waitcnt vmcnt(6)
	v_mfma_f32_16x16x32_bf16 v[12:15], v[212:215], v[30:33], v[12:15]
	s_waitcnt vmcnt(4)
	v_mfma_f32_16x16x32_bf16 v[8:11], v[216:219], v[30:33], v[8:11]
	s_waitcnt vmcnt(2)
	v_mfma_f32_16x16x32_bf16 v[4:7], v[220:223], v[30:33], v[4:7]
	s_waitcnt vmcnt(0)
	v_mfma_f32_16x16x32_bf16 v[0:3], v[224:227], v[30:33], v[0:3]
	v_add_f32_e64 v30, v52, v24
	v_add_f32_e64 v31, v53, v25
	v_pk_add_f32 v[30:31], v[30:31], v[30:31] op_sel_hi:[0,1]
	v_mov_b32_e32 v57, v31
	v_pk_add_f32 v[30:31], v[54:55], v[56:57]
	s_nop 0
	v_add_f32_e32 v24, v30, v31
	v_fmac_f32_e32 v24, v62, v58
	s_andn2_b64 exec, exec, s[26:27]
	s_cbranch_execnz .LBB0_54
	s_or_b64 exec, exec, s[26:27]
